# XCD-local barrier with a two-level arrival tree (4 sub-counters of 8 workgroups in separate 64-byte lines, then a 4-way top counter that everyone polls)
# baseline (speedup 1.0000x reference)
.LBB0_686:
	s_andn2_b64 vcc, exec, s[0:1]
	s_cbranch_vccnz .LBB0_145
	s_waitcnt vmcnt(0)
	s_waitcnt lgkmcnt(0)
	s_barrier
	s_mov_b64 s[0:1], exec
	v_readlane_b32 s2, v254, 4
	v_readlane_b32 s3, v254, 5
	s_and_b64 s[2:3], s[0:1], s[2:3]
	s_mov_b64 exec, s[2:3]
	s_cbranch_execz .LBB0_144
	v_readlane_b32 s4, v255, 60
	s_lshr_b32 s5, 0x7fd6, s75
	s_and_b32 s5, s5, 1
	s_nop 0
	s_cmp_eq_u32 s4, 0
	s_cselect_b32 s5, s5, 0
	s_cmp_eq_u32 s5, 1
	s_cbranch_scc0 .Lfb_std
	v_readlane_b32 s2, v254, 52
	v_readlane_b32 s3, v254, 53
	v_readlane_b32 s4, v255, 10
	v_readlane_b32 s5, v255, 61
	s_nop 3
	s_bfe_u32 s4, s4, 0x20003
	s_lshl_b32 s4, s4, 6
	s_add_u32 s6, s2, 0xfffff800
	s_addc_u32 s7, s3, -1
	s_add_u32 s6, s6, s4
	s_addc_u32 s7, s7, 0
	s_add_u32 s2, s2, 0x800
	s_addc_u32 s3, s3, 0
	v_mov_b32_e32 v1, 1
	s_add_i32 s5, s5, 1
	s_nop 0
	global_atomic_add v2, v0, v1, s[6:7] sc0
	v_writelane_b32 v255, s5, 61
	s_waitcnt vmcnt(0)
	buffer_inv sc1
	v_readfirstlane_b32 s4, v2
	s_lshl_b32 s6, s5, 3
	s_nop 2
	s_add_i32 s4, s4, 1
	s_cmp_eq_u32 s4, s6
	s_cbranch_scc0 .Lfb_poll
	global_atomic_add v0, v1, s[2:3]
.Lfb_poll:
	s_lshl_b32 s5, s5, 2
	s_mov_b32 s4, 0
